# best_v5 with a leaner attention tile loop (slot offsets rotate in three SGPRs, one LDS wait per 4-MFMA group)
# baseline (speedup 1.0000x reference)
.LBB0_987:
	s_waitcnt lgkmcnt(0)
	v_add_f32_e32 v2, v2, v3
	v_mul_f32_e32 v3, 0x4f800000, v2
	v_cmp_gt_f32_e32 vcc, s36, v2
	s_lshl_b32 s26, s42, 7
	s_add_i32 s42, s29, 0x2000
	v_cndmask_b32_e32 v2, v2, v3, vcc
	v_sqrt_f32_e32 v3, v2
	v_mov_b32_e32 v139, 0
	v_lshl_add_u32 v141, s41, 13, v154
	v_mov_b32_e32 v7, v139
	v_add_u32_e32 v5, -1, v3
	v_fma_f32 v6, -v5, v3, v2
	v_cmp_ge_f32_e64 s[4:5], 0, v6
	v_add_u32_e32 v6, 1, v3
	v_mov_b32_e32 v8, v139
	v_cndmask_b32_e64 v5, v3, v5, s[4:5]
	v_fma_f32 v3, -v6, v3, v2
	v_cmp_lt_f32_e64 s[4:5], 0, v3
	v_mov_b32_e32 v9, v139
	v_mov_b32_e32 v10, v139
	v_cndmask_b32_e64 v3, v5, v6, s[4:5]
	v_mul_f32_e32 v5, 0x37800000, v3
	v_cndmask_b32_e32 v3, v3, v5, vcc
	v_cmp_class_f32_e32 vcc, v2, v156
	s_add_i32 s4, s44, 1
	s_and_b32 s5, s45, 0x3ffffff0
	v_cndmask_b32_e32 v2, v3, v2, vcc
	v_mul_f32_e64 v66, v2, -v4
	v_lshl_add_u64 v[2:3], s[22:23], 0, v[134:135]
	s_add_u32 s22, s6, s5
	s_addc_u32 s23, 0, 0
	v_lshl_add_u64 v[144:145], v[2:3], 0, s[22:23]
	s_add_u32 s22, s6, s28
	s_addc_u32 s23, 0, 0
	s_lshl_b32 s5, s43, 9
	s_and_b32 s5, s5, 0x18000
	v_lshl_or_b32 v4, v155, 1, s5
	v_mov_b32_e32 v5, v131
	v_lshl_add_u64 v[2:3], s[24:25], 0, v[136:137]
	v_lshl_add_u64 v[4:5], s[22:23], 0, v[4:5]
	v_mov_b32_e32 v67, v66
	v_mov_b32_e32 v68, v66
	v_mov_b32_e32 v69, v66
	v_mov_b32_e32 v70, v66
	v_mov_b32_e32 v71, v66
	v_mov_b32_e32 v72, v66
	v_mov_b32_e32 v73, v66
	v_mov_b32_e32 v74, v66
	v_mov_b32_e32 v75, v66
	v_mov_b32_e32 v76, v66
	v_mov_b32_e32 v77, v66
	v_mov_b32_e32 v78, v66
	v_mov_b32_e32 v79, v66
	v_mov_b32_e32 v80, v66
	v_mov_b32_e32 v81, v66
	v_lshl_add_u64 v[146:147], v[2:3], 0, v[4:5]
	s_mov_b32 s6, 0
	v_mov_b32_e32 v2, 0
	v_mov_b32_e32 v3, v139
	v_mov_b32_e32 v4, v139
	v_mov_b32_e32 v5, v139
	v_mov_b32_e32 v6, v139
	v_mov_b32_e32 v11, v139
	v_mov_b32_e32 v12, v139
	v_mov_b32_e32 v13, v139
	v_mov_b32_e32 v14, v139
	v_mov_b32_e32 v15, v139
	v_mov_b32_e32 v16, v139
	v_mov_b32_e32 v17, v139
	v_mov_b32_e32 v18, 0
	v_mov_b32_e32 v19, v139
	v_mov_b32_e32 v20, v139
	v_mov_b32_e32 v21, v139
	v_mov_b32_e32 v22, v139
	v_mov_b32_e32 v23, v139
	v_mov_b32_e32 v24, v139
	v_mov_b32_e32 v25, v139
	v_mov_b32_e32 v26, v139
	v_mov_b32_e32 v27, v139
	v_mov_b32_e32 v28, v139
	v_mov_b32_e32 v29, v139
	v_mov_b32_e32 v30, v139
	v_mov_b32_e32 v31, v139
	v_mov_b32_e32 v32, v139
	v_mov_b32_e32 v33, v139
	v_mov_b32_e32 v34, 0
	v_mov_b32_e32 v35, v139
	v_mov_b32_e32 v36, v139
	v_mov_b32_e32 v37, v139
	v_mov_b32_e32 v38, v139
	v_mov_b32_e32 v39, v139
	v_mov_b32_e32 v40, v139
	v_mov_b32_e32 v41, v139
	v_mov_b32_e32 v42, v139
	v_mov_b32_e32 v43, v139
	v_mov_b32_e32 v44, v139
	v_mov_b32_e32 v45, v139
	v_mov_b32_e32 v46, v139
	v_mov_b32_e32 v47, v139
	v_mov_b32_e32 v48, v139
	v_mov_b32_e32 v49, v139
	v_mov_b32_e32 v50, 0
	v_mov_b32_e32 v51, v139
	v_mov_b32_e32 v52, v139
	v_mov_b32_e32 v53, v139
	v_mov_b32_e32 v54, v139
	v_mov_b32_e32 v55, v139
	v_mov_b32_e32 v56, v139
	v_mov_b32_e32 v57, v139
	v_mov_b32_e32 v58, v139
	v_mov_b32_e32 v59, v139
	v_mov_b32_e32 v60, v139
	v_mov_b32_e32 v61, v139
	v_mov_b32_e32 v62, v139
	v_mov_b32_e32 v63, v139
	v_mov_b32_e32 v64, v139
	v_mov_b32_e32 v65, v139
	s_movk_i32 s23, 0x4000
	s_mov_b32 s28, m0
	s_add_i32 s24, s23, s29
	s_mov_b32 m0, s24
	s_add_i32 s25, s23, s42
	global_load_lds_dwordx4 v[144:145], off
	s_addk_i32 s25, 0xff80
	s_mov_b32 m0, s25
	s_add_i32 s24, s24, 0xc000
	global_load_lds_dwordx4 v[144:145], off offset:128
	s_mov_b32 m0, s24
	s_add_i32 s25, s25, 0xc000
	global_load_lds_dwordx4 v[146:147], off
	s_mov_b32 m0, s25
	v_lshl_add_u64 v[144:145], v[144:145], 0, s[18:19]
	global_load_lds_dwordx4 v[146:147], off offset:128
	s_mov_b32 m0, s28
	v_lshl_add_u64 v[146:147], v[146:147], 0, s[18:19]
	s_waitcnt vmcnt(4) lgkmcnt(0)
	s_barrier
	v_mov_b32_e32 v159, v141
	ds_read_b128 v[210:213], v159
	ds_read_b128 v[214:217], v159 offset:512
	ds_read_b128 v[218:221], v159 offset:2048
	ds_read_b128 v[222:225], v159 offset:2560
	ds_read_b128 v[226:229], v159 offset:4096
	ds_read_b128 v[230:233], v159 offset:4608
	ds_read_b128 v[234:237], v159 offset:6144
	ds_read_b128 v[238:241], v159 offset:6656
	s_waitcnt lgkmcnt(7)
	v_mfma_f32_32x32x16_bf16 v[98:113], v[210:213], v[126:129], v[66:81]
	s_waitcnt lgkmcnt(5)
	v_mfma_f32_32x32x16_bf16 v[98:113], v[218:221], v[122:125], v[98:113]
	s_waitcnt lgkmcnt(3)
	v_mfma_f32_32x32x16_bf16 v[98:113], v[226:229], v[118:121], v[98:113]
	s_waitcnt lgkmcnt(1)
	v_mfma_f32_32x32x16_bf16 v[98:113], v[234:237], v[114:117], v[98:113]
	v_mfma_f32_32x32x16_bf16 v[82:97], v[214:217], v[126:129], v[66:81]
	v_mfma_f32_32x32x16_bf16 v[82:97], v[222:225], v[122:125], v[82:97]
	v_mfma_f32_32x32x16_bf16 v[82:97], v[230:233], v[118:121], v[82:97]
	s_waitcnt lgkmcnt(0)
	v_mfma_f32_32x32x16_bf16 v[82:97], v[238:241], v[114:117], v[82:97]
	s_nop 6
	v_exp_f32_e32 v98, v98
	v_exp_f32_e32 v99, v99
	v_exp_f32_e32 v100, v100
	v_exp_f32_e32 v101, v101
	v_exp_f32_e32 v102, v102
	v_exp_f32_e32 v103, v103
	v_exp_f32_e32 v104, v104
	v_exp_f32_e32 v105, v105
	v_exp_f32_e32 v106, v106
	v_exp_f32_e32 v107, v107
	v_exp_f32_e32 v108, v108
	v_exp_f32_e32 v109, v109
	v_exp_f32_e32 v110, v110
	v_exp_f32_e32 v111, v111
	v_exp_f32_e32 v112, v112
	v_exp_f32_e32 v113, v113
	v_exp_f32_e32 v82, v82
	v_exp_f32_e32 v83, v83
	v_exp_f32_e32 v84, v84
	v_exp_f32_e32 v85, v85
	v_exp_f32_e32 v86, v86
	v_exp_f32_e32 v87, v87
	v_exp_f32_e32 v88, v88
	v_exp_f32_e32 v89, v89
	v_exp_f32_e32 v90, v90
	v_exp_f32_e32 v91, v91
	v_exp_f32_e32 v92, v92
	v_exp_f32_e32 v93, v93
	v_exp_f32_e32 v94, v94
	v_exp_f32_e32 v95, v95
	v_exp_f32_e32 v96, v96
	v_exp_f32_e32 v97, v97
	v_cvt_pk_bf16_f32 v194, v98, v99
	v_cvt_pk_bf16_f32 v195, v100, v101
	v_cvt_pk_bf16_f32 v196, v102, v103
	v_cvt_pk_bf16_f32 v197, v104, v105
	v_cvt_pk_bf16_f32 v198, v106, v107
	v_cvt_pk_bf16_f32 v199, v108, v109
	v_cvt_pk_bf16_f32 v200, v110, v111
	v_cvt_pk_bf16_f32 v201, v112, v113
	v_cvt_pk_bf16_f32 v202, v82, v83
	v_cvt_pk_bf16_f32 v203, v84, v85
	v_cvt_pk_bf16_f32 v204, v86, v87
	v_cvt_pk_bf16_f32 v205, v88, v89
	v_cvt_pk_bf16_f32 v206, v90, v91
	v_cvt_pk_bf16_f32 v207, v92, v93
	v_cvt_pk_bf16_f32 v208, v94, v95
	v_cvt_pk_bf16_f32 v209, v96, v97
	s_mov_b32 s6, 0
	s_movk_i32 s22, 0x4000
	s_mov_b32 s23, 0x8000
.Lat3_loop:
	v_add_u32_e32 v248, s6, v153
	v_add_u32_e32 v159, s22, v141
	ds_read_b64_tr_b16 v[168:169], v248 offset:49152
	ds_read_b64_tr_b16 v[170:171], v248 offset:49664
	ds_read_b64_tr_b16 v[172:173], v248 offset:53248
	ds_read_b64_tr_b16 v[174:175], v248 offset:53760
	ds_read_b64_tr_b16 v[176:177], v248 offset:57344
	ds_read_b64_tr_b16 v[178:179], v248 offset:57856
	ds_read_b64_tr_b16 v[180:181], v248 offset:61440
	ds_read_b64_tr_b16 v[182:183], v248 offset:61952
	s_waitcnt vmcnt(0)
	s_barrier
	ds_read_b128 v[210:213], v159
	ds_read_b128 v[218:221], v159 offset:2048
	ds_read_b128 v[226:229], v159 offset:4096
	ds_read_b128 v[234:237], v159 offset:6144
	s_cmp_eq_u32 s4, 1
	s_cbranch_scc1 .Lat3_nodma
	s_mov_b32 s28, m0
	s_add_i32 s24, s23, s29
	s_mov_b32 m0, s24
	s_add_i32 s25, s23, s42
	global_load_lds_dwordx4 v[144:145], off
	s_addk_i32 s25, 0xff80
	s_mov_b32 m0, s25
	s_add_i32 s24, s24, 0xc000
	global_load_lds_dwordx4 v[144:145], off offset:128
	s_mov_b32 m0, s24
	s_add_i32 s25, s25, 0xc000
	global_load_lds_dwordx4 v[146:147], off
	s_mov_b32 m0, s25
	v_lshl_add_u64 v[144:145], v[144:145], 0, s[18:19]
	global_load_lds_dwordx4 v[146:147], off offset:128
	s_mov_b32 m0, s28
	v_lshl_add_u64 v[146:147], v[146:147], 0, s[18:19]
.Lat3_nodma:
	s_waitcnt lgkmcnt(4)
	v_mfma_f32_32x32x16_bf16 v[50:65], v[168:171], v[194:197], v[50:65]
	ds_read_b128 v[214:217], v159 offset:512
	ds_read_b128 v[222:225], v159 offset:2560
	v_add_f32_e32 v246, 0, v98
	v_add_f32_e32 v246, v99, v246
	v_add_f32_e32 v246, v100, v246
	v_add_f32_e32 v246, v101, v246
	v_add_f32_e32 v247, 0, v82
	v_add_f32_e32 v247, v83, v247
	v_mfma_f32_32x32x16_bf16 v[34:49], v[172:175], v[194:197], v[34:49]
	ds_read_b128 v[230:233], v159 offset:4608
	ds_read_b128 v[238:241], v159 offset:6656
	v_add_f32_e32 v246, v102, v246
	v_add_f32_e32 v246, v103, v246
	v_add_f32_e32 v246, v104, v246
	v_add_f32_e32 v246, v105, v246
	v_add_f32_e32 v247, v84, v247
	v_add_f32_e32 v247, v85, v247
	v_mfma_f32_32x32x16_bf16 v[18:33], v[176:179], v[194:197], v[18:33]
	v_add_f32_e32 v246, v106, v246
	v_add_f32_e32 v246, v107, v246
	v_add_f32_e32 v246, v108, v246
	v_add_f32_e32 v246, v109, v246
	v_add_f32_e32 v247, v86, v247
	v_add_f32_e32 v247, v87, v247
	v_mfma_f32_32x32x16_bf16 v[2:17], v[180:183], v[194:197], v[2:17]
	v_add_f32_e32 v246, v110, v246
	v_add_f32_e32 v246, v111, v246
	v_add_f32_e32 v246, v112, v246
	v_add_f32_e32 v246, v113, v246
	v_add_f32_e32 v247, v88, v247
	v_add_f32_e32 v247, v89, v247
	v_add_f32_e32 v246, v139, v246
	ds_read_b64_tr_b16 v[184:185], v248 offset:50176
	ds_read_b64_tr_b16 v[186:187], v248 offset:50688
	ds_read_b64_tr_b16 v[188:189], v248 offset:54272
	ds_read_b64_tr_b16 v[190:191], v248 offset:54784
	s_waitcnt lgkmcnt(8)
	v_mfma_f32_32x32x16_bf16 v[98:113], v[210:213], v[126:129], v[66:81]
	v_add_f32_e32 v247, v90, v247
	v_add_f32_e32 v247, v91, v247
	v_mfma_f32_32x32x16_bf16 v[98:113], v[218:221], v[122:125], v[98:113]
	v_add_f32_e32 v247, v92, v247
	v_add_f32_e32 v247, v93, v247
	v_mfma_f32_32x32x16_bf16 v[98:113], v[226:229], v[118:121], v[98:113]
	v_add_f32_e32 v247, v94, v247
	v_add_f32_e32 v247, v95, v247
	v_mfma_f32_32x32x16_bf16 v[98:113], v[234:237], v[114:117], v[98:113]
	v_add_f32_e32 v247, v96, v247
	v_add_f32_e32 v247, v97, v247
	v_add_f32_e32 v139, v246, v247
	ds_read_b64_tr_b16 v[160:161], v248 offset:58368
	ds_read_b64_tr_b16 v[162:163], v248 offset:58880
	ds_read_b64_tr_b16 v[242:243], v248 offset:62464
	ds_read_b64_tr_b16 v[244:245], v248 offset:62976
	s_waitcnt lgkmcnt(4)
	v_mfma_f32_32x32x16_bf16 v[50:65], v[184:187], v[198:201], v[50:65]
	v_mfma_f32_32x32x16_bf16 v[34:49], v[188:191], v[198:201], v[34:49]
	ds_read_b64_tr_b16 v[168:169], v248 offset:51200
	ds_read_b64_tr_b16 v[170:171], v248 offset:51712
	ds_read_b64_tr_b16 v[172:173], v248 offset:55296
	ds_read_b64_tr_b16 v[174:175], v248 offset:55808
	s_waitcnt lgkmcnt(4)
	v_mfma_f32_32x32x16_bf16 v[18:33], v[160:163], v[198:201], v[18:33]
	v_exp_f32_e32 v98, v98
	v_exp_f32_e32 v99, v99
	v_exp_f32_e32 v100, v100
	v_mfma_f32_32x32x16_bf16 v[2:17], v[242:245], v[198:201], v[2:17]
	ds_read_b64_tr_b16 v[176:177], v248 offset:59392
	ds_read_b64_tr_b16 v[178:179], v248 offset:59904
	ds_read_b64_tr_b16 v[180:181], v248 offset:63488
	ds_read_b64_tr_b16 v[182:183], v248 offset:64000
	v_exp_f32_e32 v101, v101
	v_exp_f32_e32 v102, v102
	v_mfma_f32_32x32x16_bf16 v[82:97], v[214:217], v[126:129], v[66:81]
	ds_read_b64_tr_b16 v[184:185], v248 offset:52224
	ds_read_b64_tr_b16 v[186:187], v248 offset:52736
	ds_read_b64_tr_b16 v[188:189], v248 offset:56320
	ds_read_b64_tr_b16 v[190:191], v248 offset:56832
	v_exp_f32_e32 v103, v103
	v_exp_f32_e32 v104, v104
	v_mfma_f32_32x32x16_bf16 v[82:97], v[222:225], v[122:125], v[82:97]
	v_exp_f32_e32 v105, v105
	v_exp_f32_e32 v106, v106
	v_exp_f32_e32 v107, v107
	v_mfma_f32_32x32x16_bf16 v[82:97], v[230:233], v[118:121], v[82:97]
	v_exp_f32_e32 v108, v108
	v_exp_f32_e32 v109, v109
	v_exp_f32_e32 v110, v110
	v_mfma_f32_32x32x16_bf16 v[82:97], v[238:241], v[114:117], v[82:97]
	v_exp_f32_e32 v111, v111
	v_exp_f32_e32 v112, v112
	v_exp_f32_e32 v113, v113
	s_waitcnt lgkmcnt(4)
	v_mfma_f32_32x32x16_bf16 v[50:65], v[168:171], v[202:205], v[50:65]
	v_cvt_pk_bf16_f32 v194, v98, v99
	v_cvt_pk_bf16_f32 v195, v100, v101
	v_cvt_pk_bf16_f32 v196, v102, v103
	v_cvt_pk_bf16_f32 v197, v104, v105
	v_mfma_f32_32x32x16_bf16 v[34:49], v[172:175], v[202:205], v[34:49]
	ds_read_b64_tr_b16 v[160:161], v248 offset:60416
	ds_read_b64_tr_b16 v[162:163], v248 offset:60928
	ds_read_b64_tr_b16 v[242:243], v248 offset:64512
	ds_read_b64_tr_b16 v[244:245], v248 offset:65024
	v_cvt_pk_bf16_f32 v198, v106, v107
	v_cvt_pk_bf16_f32 v199, v108, v109
	v_cvt_pk_bf16_f32 v200, v110, v111
	v_cvt_pk_bf16_f32 v201, v112, v113
	v_mfma_f32_32x32x16_bf16 v[18:33], v[176:179], v[202:205], v[18:33]
	v_exp_f32_e32 v82, v82
	v_exp_f32_e32 v83, v83
	v_exp_f32_e32 v84, v84
	v_mfma_f32_32x32x16_bf16 v[2:17], v[180:183], v[202:205], v[2:17]
	v_exp_f32_e32 v85, v85
	v_exp_f32_e32 v86, v86
	v_exp_f32_e32 v87, v87
	s_waitcnt lgkmcnt(4)
	v_mfma_f32_32x32x16_bf16 v[50:65], v[184:187], v[206:209], v[50:65]
	v_exp_f32_e32 v88, v88
	v_exp_f32_e32 v89, v89
	v_exp_f32_e32 v90, v90
	v_mfma_f32_32x32x16_bf16 v[34:49], v[188:191], v[206:209], v[34:49]
	v_exp_f32_e32 v91, v91
	v_exp_f32_e32 v92, v92
	v_exp_f32_e32 v93, v93
	s_waitcnt lgkmcnt(0)
	v_mfma_f32_32x32x16_bf16 v[18:33], v[160:163], v[206:209], v[18:33]
	v_exp_f32_e32 v94, v94
	v_exp_f32_e32 v95, v95
	v_exp_f32_e32 v96, v96
	v_mfma_f32_32x32x16_bf16 v[2:17], v[242:245], v[206:209], v[2:17]
	v_exp_f32_e32 v97, v97
	v_cvt_pk_bf16_f32 v202, v82, v83
	v_cvt_pk_bf16_f32 v203, v84, v85
	v_cvt_pk_bf16_f32 v204, v86, v87
	v_cvt_pk_bf16_f32 v205, v88, v89
	v_cvt_pk_bf16_f32 v206, v90, v91
	v_cvt_pk_bf16_f32 v207, v92, v93
	v_cvt_pk_bf16_f32 v208, v94, v95
	v_cvt_pk_bf16_f32 v209, v96, v97
	s_mov_b32 s24, s6
	s_mov_b32 s6, s22
	s_mov_b32 s22, s23
	s_mov_b32 s23, s24
	s_add_i32 s4, s4, -1
	s_cmp_eq_u32 s4, 0
	s_cbranch_scc0 .Lat3_loop
	v_add_u32_e32 v248, s6, v153
	ds_read_b64_tr_b16 v[168:169], v248 offset:49152
	ds_read_b64_tr_b16 v[170:171], v248 offset:49664
	ds_read_b64_tr_b16 v[172:173], v248 offset:53248
	ds_read_b64_tr_b16 v[174:175], v248 offset:53760
	ds_read_b64_tr_b16 v[176:177], v248 offset:57344
	ds_read_b64_tr_b16 v[178:179], v248 offset:57856
	ds_read_b64_tr_b16 v[180:181], v248 offset:61440
	ds_read_b64_tr_b16 v[182:183], v248 offset:61952
	s_waitcnt lgkmcnt(6)
	v_mfma_f32_32x32x16_bf16 v[50:65], v[168:171], v[194:197], v[50:65]
	v_add_f32_e32 v246, 0, v98
	v_add_f32_e32 v247, 0, v82
	v_add_f32_e32 v246, v99, v246
	v_add_f32_e32 v247, v83, v247
	s_waitcnt lgkmcnt(4)
	v_mfma_f32_32x32x16_bf16 v[34:49], v[172:175], v[194:197], v[34:49]
	ds_read_b64_tr_b16 v[184:185], v248 offset:50176
	ds_read_b64_tr_b16 v[186:187], v248 offset:50688
	ds_read_b64_tr_b16 v[188:189], v248 offset:54272
	ds_read_b64_tr_b16 v[190:191], v248 offset:54784
	v_add_f32_e32 v246, v100, v246
	v_add_f32_e32 v247, v84, v247
	v_add_f32_e32 v246, v101, v246
	v_add_f32_e32 v247, v85, v247
	s_waitcnt lgkmcnt(6)
	v_mfma_f32_32x32x16_bf16 v[18:33], v[176:179], v[194:197], v[18:33]
	v_add_f32_e32 v246, v102, v246
	v_add_f32_e32 v247, v86, v247
	v_add_f32_e32 v246, v103, v246
	v_add_f32_e32 v247, v87, v247
	s_waitcnt lgkmcnt(4)
	v_mfma_f32_32x32x16_bf16 v[2:17], v[180:183], v[194:197], v[2:17]
	ds_read_b64_tr_b16 v[160:161], v248 offset:58368
	ds_read_b64_tr_b16 v[162:163], v248 offset:58880
	ds_read_b64_tr_b16 v[242:243], v248 offset:62464
	ds_read_b64_tr_b16 v[244:245], v248 offset:62976
	v_add_f32_e32 v246, v104, v246
	v_add_f32_e32 v247, v88, v247
	v_add_f32_e32 v246, v105, v246
	v_add_f32_e32 v247, v89, v247
	s_waitcnt lgkmcnt(6)
	v_mfma_f32_32x32x16_bf16 v[50:65], v[184:187], v[198:201], v[50:65]
	v_add_f32_e32 v246, v106, v246
	v_add_f32_e32 v247, v90, v247
	v_add_f32_e32 v246, v107, v246
	v_add_f32_e32 v247, v91, v247
	s_waitcnt lgkmcnt(4)
	v_mfma_f32_32x32x16_bf16 v[34:49], v[188:191], v[198:201], v[34:49]
	ds_read_b64_tr_b16 v[168:169], v248 offset:51200
	ds_read_b64_tr_b16 v[170:171], v248 offset:51712
	ds_read_b64_tr_b16 v[172:173], v248 offset:55296
	ds_read_b64_tr_b16 v[174:175], v248 offset:55808
	v_add_f32_e32 v246, v108, v246
	v_add_f32_e32 v247, v92, v247
	v_add_f32_e32 v246, v109, v246
	v_add_f32_e32 v247, v93, v247
	s_waitcnt lgkmcnt(6)
	v_mfma_f32_32x32x16_bf16 v[18:33], v[160:163], v[198:201], v[18:33]
	v_add_f32_e32 v246, v110, v246
	v_add_f32_e32 v247, v94, v247
	v_add_f32_e32 v246, v111, v246
	v_add_f32_e32 v247, v95, v247
	s_waitcnt lgkmcnt(4)
	v_mfma_f32_32x32x16_bf16 v[2:17], v[242:245], v[198:201], v[2:17]
	ds_read_b64_tr_b16 v[176:177], v248 offset:59392
	ds_read_b64_tr_b16 v[178:179], v248 offset:59904
	ds_read_b64_tr_b16 v[180:181], v248 offset:63488
	ds_read_b64_tr_b16 v[182:183], v248 offset:64000
	v_add_f32_e32 v246, v112, v246
	v_add_f32_e32 v247, v96, v247
	v_add_f32_e32 v246, v113, v246
	v_add_f32_e32 v247, v97, v247
	v_add_f32_e32 v246, v139, v246
	v_add_f32_e32 v139, v246, v247
	v_mov_b32_e32 v90, v139
	ds_bpermute_b32 v91, v1, v90
	s_cmp_eq_u32 s41, 0
	s_cselect_b64 s[4:5], -1, 0
	s_waitcnt lgkmcnt(7)
	v_mfma_f32_32x32x16_bf16 v[50:65], v[168:171], v[202:205], v[50:65]
	s_waitcnt lgkmcnt(5)
	v_mfma_f32_32x32x16_bf16 v[34:49], v[172:175], v[202:205], v[34:49]
	ds_read_b64_tr_b16 v[184:185], v248 offset:52224
	ds_read_b64_tr_b16 v[186:187], v248 offset:52736
	ds_read_b64_tr_b16 v[188:189], v248 offset:56320
	ds_read_b64_tr_b16 v[190:191], v248 offset:56832
	s_waitcnt lgkmcnt(7)
	v_mfma_f32_32x32x16_bf16 v[18:33], v[176:179], v[202:205], v[18:33]
	s_waitcnt lgkmcnt(5)
	v_mfma_f32_32x32x16_bf16 v[2:17], v[180:183], v[202:205], v[2:17]
	ds_read_b64_tr_b16 v[160:161], v248 offset:60416
	ds_read_b64_tr_b16 v[162:163], v248 offset:60928
	ds_read_b64_tr_b16 v[242:243], v248 offset:64512
	ds_read_b64_tr_b16 v[244:245], v248 offset:65024
	s_waitcnt lgkmcnt(6)
	v_mfma_f32_32x32x16_bf16 v[50:65], v[184:187], v[206:209], v[50:65]
	s_waitcnt lgkmcnt(4)
	v_mfma_f32_32x32x16_bf16 v[34:49], v[188:191], v[206:209], v[34:49]
	s_waitcnt lgkmcnt(2)
	v_mfma_f32_32x32x16_bf16 v[18:33], v[160:163], v[206:209], v[18:33]
	s_waitcnt lgkmcnt(0)
	v_mfma_f32_32x32x16_bf16 v[2:17], v[242:245], v[206:209], v[2:17]
	v_add_f32_e32 v90, v90, v91
	v_cndmask_b32_e64 v91, v148, 1.0, s[4:5]
	v_div_scale_f32 v92, s[22:23], v90, v90, v91
	v_rcp_f32_e32 v93, v92
	s_waitcnt vmcnt(0) lgkmcnt(0)
	s_barrier
	v_fma_f32 v74, -v92, v93, 1.0
	v_fmac_f32_e32 v93, v74, v93
	v_div_scale_f32 v74, vcc, v91, v90, v91
	v_mul_f32_e32 v75, v74, v93
	v_fma_f32 v76, -v92, v75, v74
	v_fmac_f32_e32 v75, v76, v93
	v_fma_f32 v66, -v92, v75, v74
	s_nop 0
	v_div_fmas_f32 v66, v66, v93, v75
	v_div_fixup_f32 v82, v66, v90, v91
	v_lshl_add_u32 v70, s27, 13, v150
	s_and_b64 vcc, exec, s[4:5]
	s_cbranch_vccnz .LBB0_991
	v_mul_f32_e32 v66, v50, v82
	v_mul_f32_e32 v67, v51, v82
	v_cvt_pk_f16_f32 v66, v66, v67
	v_mul_f32_e32 v67, v52, v82
	v_mul_f32_e32 v68, v53, v82
	v_cvt_pk_f16_f32 v67, v67, v68
	ds_write2st64_b32 v70, v66, v67 offset1:1
	v_mul_f32_e32 v66, v54, v82
	v_mul_f32_e32 v67, v55, v82
	v_cvt_pk_f16_f32 v66, v66, v67
	v_mul_f32_e32 v67, v56, v82
	v_mul_f32_e32 v68, v57, v82
	v_cvt_pk_f16_f32 v67, v67, v68
	ds_write2st64_b32 v70, v66, v67 offset0:2 offset1:3
	v_mul_f32_e32 v66, v58, v82
	v_mul_f32_e32 v67, v59, v82
	v_cvt_pk_f16_f32 v66, v66, v67
	v_mul_f32_e32 v67, v60, v82
	v_mul_f32_e32 v68, v61, v82
	v_cvt_pk_f16_f32 v67, v67, v68
	ds_write2st64_b32 v70, v66, v67 offset0:4 offset1:5
	v_mul_f32_e32 v66, v62, v82
	v_mul_f32_e32 v67, v63, v82
	v_cvt_pk_f16_f32 v66, v66, v67
	v_mul_f32_e32 v67, v64, v82
	v_mul_f32_e32 v68, v65, v82
	v_cvt_pk_f16_f32 v67, v67, v68
	ds_write2st64_b32 v70, v66, v67 offset0:6 offset1:7
	v_mul_f32_e32 v66, v34, v82
	v_mul_f32_e32 v67, v35, v82
	v_cvt_pk_f16_f32 v66, v66, v67
	v_mul_f32_e32 v67, v36, v82
	v_mul_f32_e32 v68, v37, v82
	v_cvt_pk_f16_f32 v67, v67, v68
	ds_write2st64_b32 v70, v66, v67 offset0:8 offset1:9
	v_mul_f32_e32 v66, v38, v82
	v_mul_f32_e32 v67, v39, v82
	v_cvt_pk_f16_f32 v66, v66, v67
	v_mul_f32_e32 v67, v40, v82
	v_mul_f32_e32 v68, v41, v82
	v_cvt_pk_f16_f32 v67, v67, v68
	ds_write2st64_b32 v70, v66, v67 offset0:10 offset1:11
	v_mul_f32_e32 v66, v42, v82
	v_mul_f32_e32 v67, v43, v82
	v_cvt_pk_f16_f32 v66, v66, v67
	v_mul_f32_e32 v67, v44, v82
	v_mul_f32_e32 v68, v45, v82
	v_cvt_pk_f16_f32 v67, v67, v68
	ds_write2st64_b32 v70, v66, v67 offset0:12 offset1:13
	v_mul_f32_e32 v66, v46, v82
	v_mul_f32_e32 v67, v47, v82
	v_cvt_pk_f16_f32 v66, v66, v67
	v_mul_f32_e32 v67, v48, v82
	v_mul_f32_e32 v68, v49, v82
	v_cvt_pk_f16_f32 v67, v67, v68
	ds_write2st64_b32 v70, v66, v67 offset0:14 offset1:15
	v_mul_f32_e32 v66, v18, v82
	v_mul_f32_e32 v67, v19, v82
	v_cvt_pk_f16_f32 v66, v66, v67
	v_mul_f32_e32 v67, v20, v82
	v_mul_f32_e32 v68, v21, v82
	v_cvt_pk_f16_f32 v67, v67, v68
	ds_write2st64_b32 v70, v66, v67 offset0:16 offset1:17
	v_mul_f32_e32 v66, v22, v82
	v_mul_f32_e32 v67, v23, v82
	v_cvt_pk_f16_f32 v66, v66, v67
	v_mul_f32_e32 v67, v24, v82
	v_mul_f32_e32 v68, v25, v82
	v_cvt_pk_f16_f32 v67, v67, v68
	ds_write2st64_b32 v70, v66, v67 offset0:18 offset1:19
	v_mul_f32_e32 v66, v26, v82
	v_mul_f32_e32 v67, v27, v82
	v_cvt_pk_f16_f32 v66, v66, v67
	v_mul_f32_e32 v67, v28, v82
	v_mul_f32_e32 v68, v29, v82
	v_cvt_pk_f16_f32 v67, v67, v68
	ds_write2st64_b32 v70, v66, v67 offset0:20 offset1:21
	v_mul_f32_e32 v66, v30, v82
	v_mul_f32_e32 v67, v31, v82
	v_cvt_pk_f16_f32 v66, v66, v67
	v_mul_f32_e32 v67, v32, v82
	v_mul_f32_e32 v68, v33, v82
	v_cvt_pk_f16_f32 v67, v67, v68
	ds_write2st64_b32 v70, v66, v67 offset0:22 offset1:23
	v_mul_f32_e32 v66, v2, v82
	v_mul_f32_e32 v67, v3, v82
	v_cvt_pk_f16_f32 v66, v66, v67
	v_mul_f32_e32 v67, v4, v82
	v_mul_f32_e32 v68, v5, v82
	v_cvt_pk_f16_f32 v67, v67, v68
	ds_write2st64_b32 v70, v66, v67 offset0:24 offset1:25
	v_mul_f32_e32 v66, v6, v82
	v_mul_f32_e32 v67, v7, v82
	v_cvt_pk_f16_f32 v66, v66, v67
	v_mul_f32_e32 v67, v8, v82
	v_mul_f32_e32 v68, v9, v82
	v_cvt_pk_f16_f32 v67, v67, v68
	ds_write2st64_b32 v70, v66, v67 offset0:26 offset1:27
	v_mul_f32_e32 v66, v10, v82
	v_mul_f32_e32 v67, v11, v82
	v_cvt_pk_f16_f32 v66, v66, v67
	v_mul_f32_e32 v67, v12, v82
	v_mul_f32_e32 v68, v13, v82
	v_cvt_pk_f16_f32 v67, v67, v68
	ds_write2st64_b32 v70, v66, v67 offset0:28 offset1:29
	v_mul_f32_e32 v66, v14, v82
	v_mul_f32_e32 v67, v15, v82
	v_cvt_pk_f16_f32 v66, v66, v67
	v_mul_f32_e32 v67, v16, v82
	v_mul_f32_e32 v68, v17, v82
	v_cvt_pk_f16_f32 v67, v67, v68
	ds_write2st64_b32 v70, v66, v67 offset0:30 offset1:31
